# P1 projection GEMM tile order remapped to 8x8 m/n blocks per XCD window for L2 locality (co-resident workgroups share the A tile)
# speedup vs baseline: 1.1716x; 1.0002x over previous
; DEVI void phase_p1(const int TIDX, const int BIDX, const int GDIM, KAP KA, unsigned char* WSB, float* OUTB, int l, unsigned char* smem) {
;     ...
;   for (int item = (BIDX & 7) * (GDIM >> 3) + (BIDX >> 3); item < 516 * 22; item += GDIM) {
;     const int mt = item / 22, nt = item % 22, m0 = mt * 128;
.LBB0_437:
	s_cmp_ge_u32 s34, 0x2c00
	s_cbranch_scc1 .Lp1_tail
	s_lshr_b32 s6, s34, 4
	s_mul_hi_u32 s6, s6, 0xba2e8ba3
	s_lshr_b32 s6, s6, 3
	s_mul_i32 s7, s6, 0xb0
	s_sub_i32 s7, s34, s7
	s_lshr_b32 s16, s7, 3
	s_and_b32 s7, s7, 7
	s_lshl_b32 s6, s6, 3
	s_add_i32 s6, s6, s7
	s_branch .Lp1_map_done
.Lp1_tail:
	s_sub_i32 s7, s34, 0x2c00
	s_lshr_b32 s16, s7, 2
	s_and_b32 s7, s7, 3
	s_add_i32 s6, s7, 0x200
.Lp1_map_done:
	s_lshl_b32 s10, s6, 7
	s_ashr_i32 s11, s10, 31
	s_lshl_b64 s[12:13], s[10:11], 11
	s_add_u32 s14, s35, s12
	s_addc_u32 s15, s36, s13
	s_add_i32 s11, s16, -14
	v_mov_b32_e32 v0, v129
	s_cmp_gt_u32 s11, 3
	s_mov_b64 s[6:7], -1
	s_cbranch_scc1 .LBB0_439
	s_and_b64 vcc, exec, s[6:7]
	s_cbranch_vccz .LBB0_436
	s_branch .LBB0_494
